# attention: K.Q^T as one tight MFMA chain; the eight V-fragment refill reads moved out of the chain into the MFMA-to-VALU hazard gap
# baseline (speedup 1.0000x reference)
.Latt_loop:
	s_waitcnt vmcnt(0)
	s_barrier
	ds_read_b128 v[64:67], v173 offset:24576
	ds_read_b128 v[68:71], v173 offset:28672
	s_mov_b32 m0, s44
	ds_read_b128 v[72:75], v171 offset:24576
	global_load_lds_dwordx4 v200, s[40:41]
	s_add_u32 m0, s44, 0x400
	ds_read_b128 v[76:79], v171 offset:28672
	global_load_lds_dwordx4 v190, s[40:41]
	s_mov_b32 m0, s45
	ds_read_b128 v[216:219], v169 offset:24576
	global_load_lds_dwordx4 v192, s[42:43]
	s_add_u32 m0, s45, 0x400
	ds_read_b128 v[220:223], v169 offset:28672
	global_load_lds_dwordx4 v194, s[42:43]
	s_add_u32 m0, s45, 0x800
	ds_read_b128 v[224:227], v167 offset:24576
	global_load_lds_dwordx4 v196, s[42:43]
	s_add_u32 m0, s45, 0xc00
	ds_read_b128 v[228:231], v167 offset:28672
	global_load_lds_dwordx4 v198, s[42:43]
	ds_read_b128 v[232:235], v173 offset:32768
	ds_read_b128 v[236:239], v173 offset:36864
	ds_read_b128 v[240:243], v173 offset:40960
	ds_read_b128 v[244:247], v173 offset:45056
	s_add_u32 s40, s40, 0x18000
	s_addc_u32 s41, s41, 0
	s_add_u32 s42, s42, 0x80
	s_addc_u32 s43, s43, 0
	s_waitcnt lgkmcnt(11)
	v_mfma_f32_32x32x16_bf16 v[112:127], v[64:67], v[140:143], v[96:111]
	s_waitcnt lgkmcnt(10)
	v_mfma_f32_32x32x16_bf16 v[80:95], v[68:71], v[140:143], v[96:111]
	s_waitcnt lgkmcnt(9)
	v_mfma_f32_32x32x16_bf16 v[112:127], v[72:75], v[136:139], v[112:127]
	s_waitcnt lgkmcnt(8)
	v_mfma_f32_32x32x16_bf16 v[80:95], v[76:79], v[136:139], v[80:95]
	s_waitcnt lgkmcnt(7)
	v_mfma_f32_32x32x16_bf16 v[112:127], v[216:219], v[132:135], v[112:127]
	s_waitcnt lgkmcnt(6)
	v_mfma_f32_32x32x16_bf16 v[80:95], v[220:223], v[132:135], v[80:95]
	s_waitcnt lgkmcnt(5)
	v_mfma_f32_32x32x16_bf16 v[112:127], v[224:227], v[128:131], v[112:127]
	s_waitcnt lgkmcnt(4)
	v_mfma_f32_32x32x16_bf16 v[80:95], v[228:231], v[128:131], v[80:95]
	ds_read_b128 v[64:67], v171 offset:32768
	ds_read_b128 v[68:71], v171 offset:36864
	ds_read_b128 v[72:75], v171 offset:40960
	ds_read_b128 v[76:79], v171 offset:45056
	ds_read_b128 v[216:219], v169 offset:32768
	ds_read_b128 v[220:223], v169 offset:36864
	ds_read_b128 v[224:227], v169 offset:40960
	ds_read_b128 v[228:231], v169 offset:45056
	s_nop 3
	v_max3_f32 v175, v112, v113, v114
	v_max3_f32 v177, v115, v116, v117
	v_max3_f32 v179, v118, v119, v120
	v_max3_f32 v181, v121, v122, v123
	v_max3_f32 v248, v124, v125, v126
	v_max3_f32 v249, v127, v80, v81
	v_max3_f32 v250, v82, v83, v84
	v_max3_f32 v251, v85, v86, v87
	v_max3_f32 v253, v88, v89, v90
	v_max3_f32 v254, v91, v92, v93
	v_max3_f32 v175, v175, v177, v179
	v_max3_f32 v181, v181, v248, v249
	v_max3_f32 v250, v250, v251, v253
	v_max3_f32 v254, v254, v94, v95
	v_max3_f32 v175, v175, v181, v250
	v_max_f32_e32 v175, v175, v254
	v_cmp_lt_f32_e32 vcc, 0x41000000, v175
	s_cbranch_vccnz .Latt_resc_a
.Latt_cont_a:
	v_exp_f32_e32 v112, v112
	v_exp_f32_e32 v113, v113
	v_exp_f32_e32 v114, v114
	v_exp_f32_e32 v115, v115
	v_exp_f32_e32 v116, v116
	v_exp_f32_e32 v117, v117
	v_exp_f32_e32 v118, v118
	v_exp_f32_e32 v119, v119
	v_add_f32_e32 v189, v189, v112
	v_add_f32_e32 v189, v189, v113
	v_add_f32_e32 v189, v189, v114
	v_add_f32_e32 v189, v189, v115
	v_add_f32_e32 v189, v189, v116
	v_add_f32_e32 v189, v189, v117
	v_add_f32_e32 v189, v189, v118
	v_add_f32_e32 v189, v189, v119
	v_cvt_pk_bf16_f32 v112, v112, v113
	v_cvt_pk_bf16_f32 v113, v114, v115
	v_cvt_pk_bf16_f32 v114, v116, v117
	v_cvt_pk_bf16_f32 v115, v118, v119
	v_exp_f32_e32 v120, v120
	v_exp_f32_e32 v121, v121
	s_waitcnt lgkmcnt(8)
	v_mfma_f32_32x32x16_bf16 v[48:63], v[232:235], v[112:115], v[48:63]
	v_exp_f32_e32 v122, v122
	v_exp_f32_e32 v123, v123
	v_exp_f32_e32 v124, v124
	v_mfma_f32_32x32x16_bf16 v[32:47], v[236:239], v[112:115], v[32:47]
	v_exp_f32_e32 v125, v125
	v_exp_f32_e32 v126, v126
	v_exp_f32_e32 v127, v127
	v_mfma_f32_32x32x16_bf16 v[16:31], v[240:243], v[112:115], v[16:31]
	v_add_f32_e32 v189, v189, v120
	v_add_f32_e32 v189, v189, v121
	v_add_f32_e32 v189, v189, v122
	v_add_f32_e32 v189, v189, v123
	v_add_f32_e32 v189, v189, v124
	v_add_f32_e32 v189, v189, v125
	v_mfma_f32_32x32x16_bf16 v[0:15], v[244:247], v[112:115], v[0:15]
	ds_read_b128 v[232:235], v167 offset:32768
	ds_read_b128 v[236:239], v167 offset:36864
	ds_read_b128 v[240:243], v167 offset:40960
	ds_read_b128 v[244:247], v167 offset:45056
	v_add_f32_e32 v189, v189, v126
	v_add_f32_e32 v189, v189, v127
	v_cvt_pk_bf16_f32 v116, v120, v121
	v_cvt_pk_bf16_f32 v117, v122, v123
	v_cvt_pk_bf16_f32 v118, v124, v125
	v_cvt_pk_bf16_f32 v119, v126, v127
	s_nop 0
	s_waitcnt lgkmcnt(8)
	v_mfma_f32_32x32x16_bf16 v[48:63], v[64:67], v[116:119], v[48:63]
	v_exp_f32_e32 v80, v80
	v_exp_f32_e32 v81, v81
	v_exp_f32_e32 v82, v82
	v_mfma_f32_32x32x16_bf16 v[32:47], v[68:71], v[116:119], v[32:47]
	v_exp_f32_e32 v83, v83
	v_exp_f32_e32 v84, v84
	v_exp_f32_e32 v85, v85
	v_mfma_f32_32x32x16_bf16 v[16:31], v[72:75], v[116:119], v[16:31]
	v_exp_f32_e32 v86, v86
	v_exp_f32_e32 v87, v87
	v_add_f32_e32 v189, v189, v80
	v_add_f32_e32 v189, v189, v81
	v_mfma_f32_32x32x16_bf16 v[0:15], v[76:79], v[116:119], v[0:15]
	v_add_f32_e32 v189, v189, v82
	v_add_f32_e32 v189, v189, v83
	v_add_f32_e32 v189, v189, v84
	v_add_f32_e32 v189, v189, v85
	v_add_f32_e32 v189, v189, v86
	v_add_f32_e32 v189, v189, v87
	v_cvt_pk_bf16_f32 v80, v80, v81
	v_cvt_pk_bf16_f32 v81, v82, v83
	v_cvt_pk_bf16_f32 v82, v84, v85
	v_cvt_pk_bf16_f32 v83, v86, v87
	s_nop 0
	s_waitcnt lgkmcnt(4)
	v_mfma_f32_32x32x16_bf16 v[48:63], v[216:219], v[80:83], v[48:63]
	v_exp_f32_e32 v88, v88
	v_exp_f32_e32 v89, v89
	v_exp_f32_e32 v90, v90
	v_mfma_f32_32x32x16_bf16 v[32:47], v[220:223], v[80:83], v[32:47]
	v_exp_f32_e32 v91, v91
	v_exp_f32_e32 v92, v92
	v_exp_f32_e32 v93, v93
	v_mfma_f32_32x32x16_bf16 v[16:31], v[224:227], v[80:83], v[16:31]
	v_exp_f32_e32 v94, v94
	v_exp_f32_e32 v95, v95
	v_add_f32_e32 v189, v189, v88
	v_add_f32_e32 v189, v189, v89
	v_mfma_f32_32x32x16_bf16 v[0:15], v[228:231], v[80:83], v[0:15]
	v_add_f32_e32 v189, v189, v90
	v_add_f32_e32 v189, v189, v91
	v_add_f32_e32 v189, v189, v92
	v_add_f32_e32 v189, v189, v93
	v_add_f32_e32 v189, v189, v94
	v_add_f32_e32 v189, v189, v95
	v_cvt_pk_bf16_f32 v84, v88, v89
	v_cvt_pk_bf16_f32 v85, v90, v91
	v_cvt_pk_bf16_f32 v86, v92, v93
	v_cvt_pk_bf16_f32 v87, v94, v95
	s_nop 0
	s_waitcnt lgkmcnt(0)
	v_mfma_f32_32x32x16_bf16 v[48:63], v[232:235], v[84:87], v[48:63]
	v_mfma_f32_32x32x16_bf16 v[32:47], v[236:239], v[84:87], v[32:47]
	v_mfma_f32_32x32x16_bf16 v[16:31], v[240:243], v[84:87], v[16:31]
	v_mfma_f32_32x32x16_bf16 v[0:15], v[244:247], v[84:87], v[0:15]
	s_waitcnt vmcnt(0)
	s_barrier
	ds_read_b128 v[64:67], v173 offset:0
	ds_read_b128 v[68:71], v173 offset:4096
	s_add_u32 m0, s44, 0x6000
	ds_read_b128 v[72:75], v171 offset:0
	global_load_lds_dwordx4 v200, s[40:41]
	s_add_u32 m0, s44, 0x6400
	ds_read_b128 v[76:79], v171 offset:4096
	global_load_lds_dwordx4 v190, s[40:41]
	s_add_u32 m0, s45, 0x6000
	ds_read_b128 v[216:219], v169 offset:0
	global_load_lds_dwordx4 v192, s[42:43]
	s_add_u32 m0, s45, 0x6400
	ds_read_b128 v[220:223], v169 offset:4096
	global_load_lds_dwordx4 v194, s[42:43]
	s_add_u32 m0, s45, 0x6800
	ds_read_b128 v[224:227], v167 offset:0
	global_load_lds_dwordx4 v196, s[42:43]
	s_add_u32 m0, s45, 0x6c00
	ds_read_b128 v[228:231], v167 offset:4096
	global_load_lds_dwordx4 v198, s[42:43]
	ds_read_b128 v[232:235], v173 offset:8192
	ds_read_b128 v[236:239], v173 offset:12288
	ds_read_b128 v[240:243], v173 offset:16384
	ds_read_b128 v[244:247], v173 offset:20480
	s_add_u32 s40, s40, 0x18000
	s_addc_u32 s41, s41, 0
	s_add_u32 s42, s42, 0x80
	s_addc_u32 s43, s43, 0
	s_waitcnt lgkmcnt(11)
	v_mfma_f32_32x32x16_bf16 v[112:127], v[64:67], v[140:143], v[96:111]
	s_waitcnt lgkmcnt(10)
	v_mfma_f32_32x32x16_bf16 v[80:95], v[68:71], v[140:143], v[96:111]
	s_waitcnt lgkmcnt(9)
	v_mfma_f32_32x32x16_bf16 v[112:127], v[72:75], v[136:139], v[112:127]
	s_waitcnt lgkmcnt(8)
	v_mfma_f32_32x32x16_bf16 v[80:95], v[76:79], v[136:139], v[80:95]
	s_waitcnt lgkmcnt(7)
	v_mfma_f32_32x32x16_bf16 v[112:127], v[216:219], v[132:135], v[112:127]
	s_waitcnt lgkmcnt(6)
	v_mfma_f32_32x32x16_bf16 v[80:95], v[220:223], v[132:135], v[80:95]
	s_waitcnt lgkmcnt(5)
	v_mfma_f32_32x32x16_bf16 v[112:127], v[224:227], v[128:131], v[112:127]
	s_waitcnt lgkmcnt(4)
	v_mfma_f32_32x32x16_bf16 v[80:95], v[228:231], v[128:131], v[80:95]
	ds_read_b128 v[64:67], v171 offset:8192
	ds_read_b128 v[68:71], v171 offset:12288
	ds_read_b128 v[72:75], v171 offset:16384
	ds_read_b128 v[76:79], v171 offset:20480
	ds_read_b128 v[216:219], v169 offset:8192
	ds_read_b128 v[220:223], v169 offset:12288
	ds_read_b128 v[224:227], v169 offset:16384
	ds_read_b128 v[228:231], v169 offset:20480
	s_nop 3
	v_max3_f32 v175, v112, v113, v114
	v_max3_f32 v177, v115, v116, v117
	v_max3_f32 v179, v118, v119, v120
	v_max3_f32 v181, v121, v122, v123
	v_max3_f32 v248, v124, v125, v126
	v_max3_f32 v249, v127, v80, v81
	v_max3_f32 v250, v82, v83, v84
	v_max3_f32 v251, v85, v86, v87
	v_max3_f32 v253, v88, v89, v90
	v_max3_f32 v254, v91, v92, v93
	v_max3_f32 v175, v175, v177, v179
	v_max3_f32 v181, v181, v248, v249
	v_max3_f32 v250, v250, v251, v253
	v_max3_f32 v254, v254, v94, v95
	v_max3_f32 v175, v175, v181, v250
	v_max_f32_e32 v175, v175, v254
	v_cmp_lt_f32_e32 vcc, 0x41000000, v175
	s_cbranch_vccnz .Latt_resc_b
